# K-loop heads aligned to 64 B (on top of v24)
# speedup vs baseline: 1.0010x; 1.0010x over previous
; #define LAS __attribute__((address_space(3)))
; #define GAS __attribute__((address_space(1)))
; __device__ __forceinline__ const bf16_t* selA(const Gemm& g, int s) { return sel3(g.A0, g.A1, g.A2, s); }
; #define PG8_BAR __builtin_amdgcn_s_barrier()
; template <class Epi, bool ALIGN_EPI, bool SP2, class Hook>
; __device__ __forceinline__ void gemm_phase(LAS unsigned char* lds, const Gemm g, const StaticOrder& S, const Epi& E, Acc& acc, const bool fresh, const Hook& H, const int wave_id) {
;     ...
;     const int aoff = lds_byte(wr * 64 + fr, fq * 8), boff = lds_byte(wc * 32 + fr, fq * 8);
;     ...
;     Unit cur, nxt; int ui = 0, rs_pm = -1, t0 = 0;
;     if (!S.next(0, cur)) return;
;     if (fresh) {
; #pragma unroll
;         for (int a = 0; a < 2; ++a)
; #pragma unroll
;             for (int b = 0; b < 2; ++b)
; #pragma unroll
;                 for (int m = 0; m < 4; ++m)
; #pragma unroll
;                     for (int n = 0; n < 2; ++n) acc[a][b][m][n] = (f32x4){0.f, 0.f, 0.f, 0.f};
;     }
;     bf16x8 At[4][2], B0[2][2], B1[2][2];
;     Src cA = make_src(selA(g, cur.seg), (size_t)cur.pm * tstepA), cB = make_src(selB(g, cur.seg), (size_t)cur.pn * tstep);
;     if constexpr (SP2) {
;         f32x4 rpa = {0.f, 0.f, 0.f, 0.f}, rpb = rpa;
;         float rsum = 0.f;
;         if constexpr (Epi::NEEDS_RS) { const GAS f32x4* p = (const GAS f32x4*)(E.rowss + (size_t)(cur.pm * BM + (tid >> 1)) * 16) + (tid & 1) * 2; rpa = p[0]; rpb = p[1]; }
;         PG8_STAGE(PG8_SB(0, 0), cB, voffB); PG8_STAGE(PG8_SB(0, 1), cB + hstep, voffB); PG8_STAGE(PG8_SA(0, 0), cA, voffA); PG8_STAGE(PG8_SA(0, 1), cA + hstepA, voffA);
;         if (wr == 1) PG8_BAR;
;         PG8_WAIT_V(2); PG8_BAR;
;         if constexpr (Epi::NEEDS_RS) {
;             rsum = ((rpa[0] + rpa[1]) + (rpa[2] + rpa[3])) + ((rpb[0] + rpb[1]) + (rpb[2] + rpb[3]));
;             const float t2 = __builtin_bit_cast(float, __builtin_amdgcn_update_dpp(0, __builtin_bit_cast(int, rsum), 0xB1  , 0xf, 0xf, false)); rsum = (tid & 1) ? (t2 + rsum) : (rsum + t2);
;             if ((tid & 1) == 0) ((LAS float*)(lds + RSTAB_OFF))[tid >> 1] = __builtin_amdgcn_rsqf(rsum * (1.0f / DM) + NORM_EPS);
;             rs_pm = cur.pm;
;         }
;         PG8_STAGE(PG8_SB(1, 0), cB + kstep, voffB); PG8_STAGE(PG8_SA(1, 0), cA + kstep, voffA); PG8_STAGE(PG8_SB(1, 1), cB + hstep + kstep, voffB);
;         PG8_WAIT_V(6); PG8_BAR;
.LBB0_381:
	s_or_b64 exec, exec, s[0:1]
	s_mov_b32 m0, s39
	v_readlane_b32 s0, v253, 42
	s_mov_b32 s10, s78
	s_mov_b32 s11, s79
	v_and_b32_e32 v0, 15, v10
	v_and_b32_e32 v3, 48, v10
	v_readlane_b32 s2, v254, 37
	buffer_load_dwordx4 v145, s[76:79], s0 offen lds
	s_mov_b32 m0, s40
	v_readlane_b32 s3, v254, 38
	buffer_load_dwordx4 v147, s[76:79], s0 offen lds
	s_mov_b32 m0, s41
	v_readlane_b32 s0, v253, 44
	s_add_u32 s20, s2, 0x400000
	s_addc_u32 s21, s3, 0
	s_add_u32 s22, s2, 0x410000
	v_readlane_b32 s52, v249, 36
	s_addc_u32 s23, s3, 0
	buffer_load_dwordx4 v144, s[8:11], s0 offen lds
	s_mov_b32 m0, s33
	v_readlane_b32 s58, v249, 42
	buffer_load_dwordx4 v146, s[8:11], s0 offen lds
	s_mov_b32 m0, s43
	v_readlane_b32 s0, v253, 46
	v_readlane_b32 s62, v249, 46
	v_readlane_b32 s59, v249, 43
	v_readlane_b32 s63, v249, 47
	s_mov_b32 s27, s73
	v_readlane_b32 s54, v249, 38
	buffer_load_dwordx4 v145, s[76:79], s0 offen lds
	s_mov_b32 m0, s42
	v_readlane_b32 s55, v249, 39
	buffer_load_dwordx4 v147, s[76:79], s0 offen lds
	v_readlane_b32 s0, v250, 1
	s_waitcnt vmcnt(6)
	v_readlane_b32 s64, v249, 48
	v_readlane_b32 s67, v249, 51
	v_or_b32_e32 v2, s0, v0
	v_lshlrev_b32_e32 v4, 6, v2
	s_movk_i32 s0, 0x3c0
	v_lshlrev_b32_e32 v2, 2, v2
	v_and_or_b32 v4, v4, s0, v3
	v_and_b32_e32 v2, 32, v2
	v_readlane_b32 s0, v250, 2
	v_lshl_or_b32 v0, v0, 6, v3
	v_mov_b32_e32 v3, v1
	v_bitop3_b32 v4, v4, s0, v2 bitop3:0xde
	v_lshlrev_b32_e32 v2, 2, v10
	v_and_b32_e32 v2, 32, v2
	v_readlane_b32 s0, v250, 4
	v_add_u32_e32 v149, 0, v4
	v_readlane_b32 s28, v253, 38
	v_bitop3_b32 v5, v0, s0, v2 bitop3:0xde
	v_readlane_b32 s0, v254, 36
	s_mul_i32 s72, s0, 0xc00
	s_lshl_b64 s[0:1], s[72:73], 2
	s_add_u32 s62, s58, s0
	s_mov_b64 s[72:73], s[2:3]
	s_addc_u32 s63, s59, s1
	s_add_u32 s24, s72, 0x7b00000
	s_addc_u32 s25, s73, 0
	s_add_u32 s30, s72, 0x7f00000
	s_addc_u32 s31, s73, 0
	v_mov_b32_e32 v2, v1
	s_add_u32 s34, s72, 0x8300000
	v_mov_b32_e32 v0, v1
	v_add_u32_e32 v148, 0, v5
	v_mov_b64_e32 v[122:123], v[2:3]
	v_mov_b64_e32 v[114:115], v[2:3]
	v_mov_b64_e32 v[102:103], v[2:3]
	v_mov_b64_e32 v[90:91], v[2:3]
	v_mov_b64_e32 v[70:71], v[2:3]
	v_mov_b64_e32 v[58:59], v[2:3]
	v_mov_b64_e32 v[38:39], v[2:3]
	v_mov_b64_e32 v[30:31], v[2:3]
	v_mov_b64_e32 v[130:131], v[2:3]
	v_mov_b64_e32 v[126:127], v[2:3]
	v_mov_b64_e32 v[118:119], v[2:3]
	v_mov_b64_e32 v[110:111], v[2:3]
	v_mov_b64_e32 v[94:95], v[2:3]
	v_mov_b64_e32 v[82:83], v[2:3]
	v_mov_b64_e32 v[66:67], v[2:3]
	v_mov_b64_e32 v[50:51], v[2:3]
	v_mov_b64_e32 v[74:75], v[2:3]
	v_mov_b64_e32 v[62:63], v[2:3]
	v_mov_b64_e32 v[42:43], v[2:3]
	v_mov_b64_e32 v[34:35], v[2:3]
	v_mov_b64_e32 v[18:19], v[2:3]
	v_mov_b64_e32 v[14:15], v[2:3]
	v_mov_b64_e32 v[10:11], v[2:3]
	v_mov_b64_e32 v[6:7], v[2:3]
	v_mov_b64_e32 v[98:99], v[2:3]
	v_mov_b64_e32 v[106:107], v[2:3]
	v_mov_b64_e32 v[86:87], v[2:3]
	v_mov_b64_e32 v[78:79], v[2:3]
	v_mov_b64_e32 v[54:55], v[2:3]
	v_mov_b64_e32 v[46:47], v[2:3]
	v_mov_b64_e32 v[26:27], v[2:3]
	v_mov_b64_e32 v[22:23], v[2:3]
	v_readlane_b32 s66, v249, 50
	s_addc_u32 s35, s73, 0
	s_mov_b32 s12, 0
	v_mov_b64_e32 v[120:121], v[0:1]
	v_mov_b64_e32 v[112:113], v[0:1]
	v_mov_b64_e32 v[100:101], v[0:1]
	v_mov_b64_e32 v[88:89], v[0:1]
	v_mov_b64_e32 v[68:69], v[0:1]
	v_mov_b64_e32 v[56:57], v[0:1]
	v_mov_b64_e32 v[36:37], v[0:1]
	v_mov_b64_e32 v[28:29], v[0:1]
	v_mov_b64_e32 v[128:129], v[0:1]
	v_mov_b64_e32 v[124:125], v[0:1]
	v_mov_b64_e32 v[116:117], v[0:1]
	v_mov_b64_e32 v[108:109], v[0:1]
	v_mov_b64_e32 v[92:93], v[0:1]
	v_mov_b64_e32 v[80:81], v[0:1]
	v_mov_b64_e32 v[64:65], v[0:1]
	v_mov_b64_e32 v[48:49], v[0:1]
	v_mov_b64_e32 v[72:73], v[0:1]
	v_mov_b64_e32 v[60:61], v[0:1]
	v_mov_b64_e32 v[40:41], v[0:1]
	v_mov_b64_e32 v[32:33], v[0:1]
	v_mov_b64_e32 v[16:17], v[0:1]
	v_mov_b64_e32 v[12:13], v[0:1]
	v_mov_b64_e32 v[8:9], v[0:1]
	v_mov_b64_e32 v[4:5], v[0:1]
	v_mov_b64_e32 v[96:97], v[0:1]
	v_readlane_b32 s70, v253, 37
	s_mov_b32 s67, s28
	s_mov_b64 s[54:55], s[78:79]
	v_readlane_b32 s13, v253, 45
	s_mov_b64 s[10:11], s[78:79]
	v_readlane_b32 s14, v253, 43
	s_mov_b32 s64, 0
	v_mov_b64_e32 v[104:105], v[0:1]
	v_mov_b64_e32 v[84:85], v[0:1]
	v_mov_b64_e32 v[76:77], v[0:1]
	v_mov_b64_e32 v[52:53], v[0:1]
	v_mov_b64_e32 v[44:45], v[0:1]
	v_mov_b64_e32 v[24:25], v[0:1]
	v_mov_b64_e32 v[20:21], v[0:1]
	v_readlane_b32 s53, v249, 37
	v_readlane_b32 s56, v249, 40
	v_readlane_b32 s57, v249, 41
	v_readlane_b32 s60, v249, 44
	v_readlane_b32 s61, v249, 45
	v_readlane_b32 s65, v249, 49
	s_barrier
	s_branch .LBB0_384
	.p2align	6

; template <class Epi, bool ALIGN_EPI, bool SP2, class Hook>
; __device__ __forceinline__ void gemm_phase(LAS unsigned char* lds, const Gemm g, const StaticOrder& S, const Epi& E, Acc& acc, const bool fresh, const Hook& H, const int wave_id) {
;     ...
;         for (int t = t0; t < nt; t += 2) {
;             const bool last = (t == nt - 2);
;             const Src a1 = cA + (size_t)(t + 1) * kstep;
;             const Src a2 = last ? nA : cA + (size_t)(t + 2) * kstep, b2 = last ? nB : cB + (size_t)(t + 2) * kstep;
;             const Src a3 = a2 + kstep, b3 = b2 + kstep;
.LBB0_390:
	s_add_i32 s29, s12, -2
	s_lshl_b32 s12, s12, 7
	s_add_i32 s14, s14, s12
	s_add_i32 s12, s13, s12
	s_add_i32 s56, s14, 0x40080
	s_add_i32 s57, s12, 0x100
	.p2align	6

; template <class Epi, bool ALIGN_EPI, bool SP2, class Hook>
; __device__ __forceinline__ void gemm_phase(LAS unsigned char* lds, const Gemm g, const StaticOrder& S, const Epi& E, Acc& acc, const bool fresh, const Hook& H, const int wave_id) {
;     ...
;         if (reset) {
; #pragma unroll
;             for (int a = 0; a < 2; ++a)
; #pragma unroll
;                 for (int b = 0; b < 2; ++b)
; #pragma unroll
;                     for (int m = 0; m < 4; ++m)
; #pragma unroll
;                         for (int n = 0; n < 2; ++n) acc[a][b][m][n] = (f32x4){0.f, 0.f, 0.f, 0.f};
;         }
.LBB0_701:
	v_mov_b32_e32 v2, 0
	s_add_i32 s55, s13, 0x20080
	s_add_i32 s56, s12, 0x100
	s_mov_b32 s57, -2
	v_mov_b32_e32 v3, v2
	v_mov_b32_e32 v4, v2
	v_mov_b32_e32 v5, v2
	v_mov_b32_e32 v6, v2
	v_mov_b32_e32 v7, v2
	v_mov_b32_e32 v8, v2
	v_mov_b32_e32 v9, v2
	v_mov_b32_e32 v18, v2
	v_mov_b32_e32 v19, v2
	v_mov_b32_e32 v20, v2
	v_mov_b32_e32 v21, v2
	v_mov_b32_e32 v22, v2
	v_mov_b32_e32 v23, v2
	v_mov_b32_e32 v24, v2
	v_mov_b32_e32 v25, v2
	v_mov_b32_e32 v38, v2
	v_mov_b32_e32 v39, v2
	v_mov_b32_e32 v40, v2
	v_mov_b32_e32 v41, v2
	v_mov_b32_e32 v42, v2
	v_mov_b32_e32 v43, v2
	v_mov_b32_e32 v44, v2
	v_mov_b32_e32 v45, v2
	v_mov_b32_e32 v62, v2
	v_mov_b32_e32 v63, v2
	v_mov_b32_e32 v64, v2
	v_mov_b32_e32 v65, v2
	v_mov_b32_e32 v66, v2
	v_mov_b32_e32 v67, v2
	v_mov_b32_e32 v68, v2
	v_mov_b32_e32 v69, v2
	v_mov_b32_e32 v10, v2
	v_mov_b32_e32 v11, v2
	v_mov_b32_e32 v12, v2
	v_mov_b32_e32 v13, v2
	v_mov_b32_e32 v14, v2
	v_mov_b32_e32 v15, v2
	v_mov_b32_e32 v16, v2
	v_mov_b32_e32 v17, v2
	v_mov_b32_e32 v26, v2
	v_mov_b32_e32 v27, v2
	v_mov_b32_e32 v28, v2
	v_mov_b32_e32 v29, v2
	v_mov_b32_e32 v30, v2
	v_mov_b32_e32 v31, v2
	v_mov_b32_e32 v32, v2
	v_mov_b32_e32 v33, v2
	v_mov_b32_e32 v50, v2
	v_mov_b32_e32 v51, v2
	v_mov_b32_e32 v52, v2
	v_mov_b32_e32 v53, v2
	v_mov_b32_e32 v54, v2
	v_mov_b32_e32 v55, v2
	v_mov_b32_e32 v56, v2
	v_mov_b32_e32 v57, v2
	v_mov_b32_e32 v74, v2
	v_mov_b32_e32 v75, v2
	v_mov_b32_e32 v76, v2
	v_mov_b32_e32 v77, v2
	v_mov_b32_e32 v78, v2
	v_mov_b32_e32 v79, v2
	v_mov_b32_e32 v80, v2
	v_mov_b32_e32 v81, v2
	v_mov_b32_e32 v86, v2
	v_mov_b32_e32 v87, v2
	v_mov_b32_e32 v88, v2
	v_mov_b32_e32 v89, v2
	v_mov_b32_e32 v90, v2
	v_mov_b32_e32 v91, v2
	v_mov_b32_e32 v92, v2
	v_mov_b32_e32 v93, v2
	v_mov_b32_e32 v110, v2
	v_mov_b32_e32 v111, v2
	v_mov_b32_e32 v112, v2
	v_mov_b32_e32 v113, v2
	v_mov_b32_e32 v114, v2
	v_mov_b32_e32 v115, v2
	v_mov_b32_e32 v116, v2
	v_mov_b32_e32 v117, v2
	v_mov_b32_e32 v134, v2
	v_mov_b32_e32 v135, v2
	v_mov_b32_e32 v136, v2
	v_mov_b32_e32 v137, v2
	v_mov_b32_e32 v138, v2
	v_mov_b32_e32 v139, v2
	v_mov_b32_e32 v140, v2
	v_mov_b32_e32 v141, v2
	v_mov_b32_e32 v158, v2
	v_mov_b32_e32 v159, v2
	v_mov_b32_e32 v160, v2
	v_mov_b32_e32 v161, v2
	v_mov_b32_e32 v162, v2
	v_mov_b32_e32 v163, v2
	v_mov_b32_e32 v164, v2
	v_mov_b32_e32 v165, v2
	v_mov_b32_e32 v98, v2
	v_mov_b32_e32 v99, v2
	v_mov_b32_e32 v100, v2
	v_mov_b32_e32 v101, v2
	v_mov_b32_e32 v102, v2
	v_mov_b32_e32 v103, v2
	v_mov_b32_e32 v104, v2
	v_mov_b32_e32 v105, v2
	v_mov_b32_e32 v122, v2
	v_mov_b32_e32 v123, v2
	v_mov_b32_e32 v124, v2
	v_mov_b32_e32 v125, v2
	v_mov_b32_e32 v126, v2
	v_mov_b32_e32 v127, v2
	v_mov_b32_e32 v128, v2
	v_mov_b32_e32 v129, v2
	v_mov_b32_e32 v146, v2
	v_mov_b32_e32 v147, v2
	v_mov_b32_e32 v148, v2
	v_mov_b32_e32 v149, v2
	v_mov_b32_e32 v150, v2
	v_mov_b32_e32 v151, v2
	v_mov_b32_e32 v152, v2
	v_mov_b32_e32 v153, v2
	v_mov_b32_e32 v170, v2
	v_mov_b32_e32 v171, v2
	v_mov_b32_e32 v172, v2
	v_mov_b32_e32 v173, v2
	v_mov_b32_e32 v178, v2
	v_mov_b32_e32 v179, v2
	v_mov_b32_e32 v180, v2
	v_mov_b32_e32 v181, v2
	.p2align	6

; template <class Epi, bool ALIGN_EPI, bool SP2, class Hook>
; __device__ __forceinline__ void gemm_phase(LAS unsigned char* lds, const Gemm g, const StaticOrder& S, const Epi& E, Acc& acc, const bool fresh, const Hook& H, const int wave_id) {
;     ...
;         for (int t = t0; t < nt; t += 2) {
;             const bool last = (t == nt - 2);
;             const Src a1 = cA + (size_t)(t + 1) * kstep;
;             const Src a2 = last ? nA : cA + (size_t)(t + 2) * kstep, b2 = last ? nB : cB + (size_t)(t + 2) * kstep;
;             const Src a3 = a2 + kstep, b3 = b2 + kstep;
.LBB0_778:
	s_add_i32 s2, s13, 0x20080
	s_add_i32 s3, s12, 0x100
	s_mov_b32 s63, -2
	.p2align	6

; template <class Epi, bool ALIGN_EPI, bool SP2, class Hook>
; __device__ __forceinline__ void gemm_phase(LAS unsigned char* lds, const Gemm g, const StaticOrder& S, const Epi& E, Acc& acc, const bool fresh, const Hook& H, const int wave_id) {
;     ...
;         if (reset) {
; #pragma unroll
;             for (int a = 0; a < 2; ++a)
; #pragma unroll
;                 for (int b = 0; b < 2; ++b)
; #pragma unroll
;                     for (int m = 0; m < 4; ++m)
; #pragma unroll
;                         for (int n = 0; n < 2; ++n) acc[a][b][m][n] = (f32x4){0.f, 0.f, 0.f, 0.f};
;         }
.LBB0_902:
	v_mov_b32_e32 v178, 0
	s_add_i32 s55, s13, 0x20080
	s_add_i32 s56, s12, 0x100
	s_mov_b32 s57, -2
	v_mov_b32_e32 v179, v178
	v_mov_b32_e32 v180, v178
	v_mov_b32_e32 v181, v178
	v_mov_b32_e32 v170, v178
	v_mov_b32_e32 v171, v178
	v_mov_b32_e32 v172, v178
	v_mov_b32_e32 v173, v178
	v_mov_b32_e32 v150, v178
	v_mov_b32_e32 v151, v178
	v_mov_b32_e32 v152, v178
	v_mov_b32_e32 v153, v178
	v_mov_b32_e32 v146, v178
	v_mov_b32_e32 v147, v178
	v_mov_b32_e32 v148, v178
	v_mov_b32_e32 v149, v178
	v_mov_b32_e32 v126, v178
	v_mov_b32_e32 v127, v178
	v_mov_b32_e32 v128, v178
	v_mov_b32_e32 v129, v178
	v_mov_b32_e32 v122, v178
	v_mov_b32_e32 v123, v178
	v_mov_b32_e32 v124, v178
	v_mov_b32_e32 v125, v178
	v_mov_b32_e32 v102, v178
	v_mov_b32_e32 v103, v178
	v_mov_b32_e32 v104, v178
	v_mov_b32_e32 v105, v178
	v_mov_b32_e32 v98, v178
	v_mov_b32_e32 v99, v178
	v_mov_b32_e32 v100, v178
	v_mov_b32_e32 v101, v178
	v_mov_b32_e32 v162, v178
	v_mov_b32_e32 v163, v178
	v_mov_b32_e32 v164, v178
	v_mov_b32_e32 v165, v178
	v_mov_b32_e32 v158, v178
	v_mov_b32_e32 v159, v178
	v_mov_b32_e32 v160, v178
	v_mov_b32_e32 v161, v178
	v_mov_b32_e32 v138, v178
	v_mov_b32_e32 v139, v178
	v_mov_b32_e32 v140, v178
	v_mov_b32_e32 v141, v178
	v_mov_b32_e32 v134, v178
	v_mov_b32_e32 v135, v178
	v_mov_b32_e32 v136, v178
	v_mov_b32_e32 v137, v178
	v_mov_b32_e32 v114, v178
	v_mov_b32_e32 v115, v178
	v_mov_b32_e32 v116, v178
	v_mov_b32_e32 v117, v178
	v_mov_b32_e32 v110, v178
	v_mov_b32_e32 v111, v178
	v_mov_b32_e32 v112, v178
	v_mov_b32_e32 v113, v178
	v_mov_b32_e32 v90, v178
	v_mov_b32_e32 v91, v178
	v_mov_b32_e32 v92, v178
	v_mov_b32_e32 v93, v178
	v_mov_b32_e32 v86, v178
	v_mov_b32_e32 v87, v178
	v_mov_b32_e32 v88, v178
	v_mov_b32_e32 v89, v178
	v_mov_b32_e32 v78, v178
	v_mov_b32_e32 v79, v178
	v_mov_b32_e32 v80, v178
	v_mov_b32_e32 v81, v178
	v_mov_b32_e32 v74, v178
	v_mov_b32_e32 v75, v178
	v_mov_b32_e32 v76, v178
	v_mov_b32_e32 v77, v178
	v_mov_b32_e32 v54, v178
	v_mov_b32_e32 v55, v178
	v_mov_b32_e32 v56, v178
	v_mov_b32_e32 v57, v178
	v_mov_b32_e32 v50, v178
	v_mov_b32_e32 v51, v178
	v_mov_b32_e32 v52, v178
	v_mov_b32_e32 v53, v178
	v_mov_b32_e32 v30, v178
	v_mov_b32_e32 v31, v178
	v_mov_b32_e32 v32, v178
	v_mov_b32_e32 v33, v178
	v_mov_b32_e32 v26, v178
	v_mov_b32_e32 v27, v178
	v_mov_b32_e32 v28, v178
	v_mov_b32_e32 v29, v178
	v_mov_b32_e32 v14, v178
	v_mov_b32_e32 v15, v178
	v_mov_b32_e32 v16, v178
	v_mov_b32_e32 v17, v178
	v_mov_b32_e32 v10, v178
	v_mov_b32_e32 v11, v178
	v_mov_b32_e32 v12, v178
	v_mov_b32_e32 v13, v178
	v_mov_b32_e32 v66, v178
	v_mov_b32_e32 v67, v178
	v_mov_b32_e32 v68, v178
	v_mov_b32_e32 v69, v178
	v_mov_b32_e32 v62, v178
	v_mov_b32_e32 v63, v178
	v_mov_b32_e32 v64, v178
	v_mov_b32_e32 v65, v178
	v_mov_b32_e32 v42, v178
	v_mov_b32_e32 v43, v178
	v_mov_b32_e32 v44, v178
	v_mov_b32_e32 v45, v178
	v_mov_b32_e32 v38, v178
	v_mov_b32_e32 v39, v178
	v_mov_b32_e32 v40, v178
	v_mov_b32_e32 v41, v178
	v_mov_b32_e32 v22, v178
	v_mov_b32_e32 v23, v178
	v_mov_b32_e32 v24, v178
	v_mov_b32_e32 v25, v178
	v_mov_b32_e32 v18, v178
	v_mov_b32_e32 v19, v178
	v_mov_b32_e32 v20, v178
	v_mov_b32_e32 v21, v178
	v_mov_b32_e32 v6, v178
	v_mov_b32_e32 v7, v178
	v_mov_b32_e32 v8, v178
	v_mov_b32_e32 v9, v178
	v_mov_b32_e32 v2, v178
	v_mov_b32_e32 v3, v178
	v_mov_b32_e32 v4, v178
	v_mov_b32_e32 v5, v178
	s_waitcnt vmcnt(0)
	.p2align	6

; template <class Epi, bool ALIGN_EPI, bool SP2, class Hook>
; __device__ __forceinline__ void gemm_phase(LAS unsigned char* lds, const Gemm g, const StaticOrder& S, const Epi& E, Acc& acc, const bool fresh, const Hook& H, const int wave_id) {
;     ...
;         for (int t = t0; t < nt; t += 2) {
;             const bool last = (t == nt - 2);
.LBB0_1029:
	.p2align	6

; template <class Epi, bool ALIGN_EPI, bool SP2, class Hook>
; __device__ __forceinline__ void gemm_phase(LAS unsigned char* lds, const Gemm g, const StaticOrder& S, const Epi& E, Acc& acc, const bool fresh, const Hook& H, const int wave_id) {
;     ...
;         if (reset) {
; #pragma unroll
;             for (int a = 0; a < 2; ++a)
; #pragma unroll
;                 for (int b = 0; b < 2; ++b)
; #pragma unroll
;                     for (int m = 0; m < 4; ++m)
; #pragma unroll
;                         for (int n = 0; n < 2; ++n) acc[a][b][m][n] = (f32x4){0.f, 0.f, 0.f, 0.f};
;         }
.LBB0_1234:
	v_mov_b32_e32 v2, 0
	s_add_i32 s2, s17, 0x40080
	s_add_i32 s3, s16, 0x100
	s_mov_b32 s59, -2
	v_mov_b32_e32 v3, v2
	v_mov_b32_e32 v4, v2
	v_mov_b32_e32 v5, v2
	v_mov_b32_e32 v6, v2
	v_mov_b32_e32 v7, v2
	v_mov_b32_e32 v8, v2
	v_mov_b32_e32 v9, v2
	v_mov_b32_e32 v18, v2
	v_mov_b32_e32 v19, v2
	v_mov_b32_e32 v20, v2
	v_mov_b32_e32 v21, v2
	v_mov_b32_e32 v22, v2
	v_mov_b32_e32 v23, v2
	v_mov_b32_e32 v24, v2
	v_mov_b32_e32 v25, v2
	v_mov_b32_e32 v34, v2
	v_mov_b32_e32 v35, v2
	v_mov_b32_e32 v36, v2
	v_mov_b32_e32 v37, v2
	v_mov_b32_e32 v38, v2
	v_mov_b32_e32 v39, v2
	v_mov_b32_e32 v40, v2
	v_mov_b32_e32 v41, v2
	v_mov_b32_e32 v50, v2
	v_mov_b32_e32 v51, v2
	v_mov_b32_e32 v52, v2
	v_mov_b32_e32 v53, v2
	v_mov_b32_e32 v54, v2
	v_mov_b32_e32 v55, v2
	v_mov_b32_e32 v56, v2
	v_mov_b32_e32 v57, v2
	v_mov_b32_e32 v10, v2
	v_mov_b32_e32 v11, v2
	v_mov_b32_e32 v12, v2
	v_mov_b32_e32 v13, v2
	v_mov_b32_e32 v14, v2
	v_mov_b32_e32 v15, v2
	v_mov_b32_e32 v16, v2
	v_mov_b32_e32 v17, v2
	v_mov_b32_e32 v26, v2
	v_mov_b32_e32 v27, v2
	v_mov_b32_e32 v28, v2
	v_mov_b32_e32 v29, v2
	v_mov_b32_e32 v30, v2
	v_mov_b32_e32 v31, v2
	v_mov_b32_e32 v32, v2
	v_mov_b32_e32 v33, v2
	v_mov_b32_e32 v42, v2
	v_mov_b32_e32 v43, v2
	v_mov_b32_e32 v44, v2
	v_mov_b32_e32 v45, v2
	v_mov_b32_e32 v46, v2
	v_mov_b32_e32 v47, v2
	v_mov_b32_e32 v48, v2
	v_mov_b32_e32 v49, v2
	v_mov_b32_e32 v58, v2
	v_mov_b32_e32 v59, v2
	v_mov_b32_e32 v60, v2
	v_mov_b32_e32 v61, v2
	v_mov_b32_e32 v62, v2
	v_mov_b32_e32 v63, v2
	v_mov_b32_e32 v64, v2
	v_mov_b32_e32 v65, v2
	v_mov_b32_e32 v66, v2
	v_mov_b32_e32 v67, v2
	v_mov_b32_e32 v68, v2
	v_mov_b32_e32 v69, v2
	v_mov_b32_e32 v70, v2
	v_mov_b32_e32 v71, v2
	v_mov_b32_e32 v72, v2
	v_mov_b32_e32 v73, v2
	v_mov_b32_e32 v82, v2
	v_mov_b32_e32 v83, v2
	v_mov_b32_e32 v84, v2
	v_mov_b32_e32 v85, v2
	v_mov_b32_e32 v86, v2
	v_mov_b32_e32 v87, v2
	v_mov_b32_e32 v88, v2
	v_mov_b32_e32 v89, v2
	v_mov_b32_e32 v98, v2
	v_mov_b32_e32 v99, v2
	v_mov_b32_e32 v100, v2
	v_mov_b32_e32 v101, v2
	v_mov_b32_e32 v102, v2
	v_mov_b32_e32 v103, v2
	v_mov_b32_e32 v104, v2
	v_mov_b32_e32 v105, v2
	v_mov_b32_e32 v114, v2
	v_mov_b32_e32 v115, v2
	v_mov_b32_e32 v116, v2
	v_mov_b32_e32 v117, v2
	v_mov_b32_e32 v118, v2
	v_mov_b32_e32 v119, v2
	v_mov_b32_e32 v120, v2
	v_mov_b32_e32 v121, v2
	v_mov_b32_e32 v74, v2
	v_mov_b32_e32 v75, v2
	v_mov_b32_e32 v76, v2
	v_mov_b32_e32 v77, v2
	v_mov_b32_e32 v78, v2
	v_mov_b32_e32 v79, v2
	v_mov_b32_e32 v80, v2
	v_mov_b32_e32 v81, v2
	v_mov_b32_e32 v90, v2
	v_mov_b32_e32 v91, v2
	v_mov_b32_e32 v92, v2
	v_mov_b32_e32 v93, v2
	v_mov_b32_e32 v94, v2
	v_mov_b32_e32 v95, v2
	v_mov_b32_e32 v96, v2
	v_mov_b32_e32 v97, v2
	v_mov_b32_e32 v106, v2
	v_mov_b32_e32 v107, v2
	v_mov_b32_e32 v108, v2
	v_mov_b32_e32 v109, v2
	v_mov_b32_e32 v110, v2
	v_mov_b32_e32 v111, v2
	v_mov_b32_e32 v112, v2
	v_mov_b32_e32 v113, v2
	v_mov_b32_e32 v122, v2
	v_mov_b32_e32 v123, v2
	v_mov_b32_e32 v124, v2
	v_mov_b32_e32 v125, v2
	v_mov_b32_e32 v126, v2
	v_mov_b32_e32 v127, v2
	v_mov_b32_e32 v128, v2
	v_mov_b32_e32 v129, v2
	s_waitcnt vmcnt(0)
	.p2align	6

; #define LAS __attribute__((address_space(3)))
; #define GAS __attribute__((address_space(1)))
; __device__ __forceinline__ const bf16_t* selA(const Gemm& g, int s) { return sel3(g.A0, g.A1, g.A2, s); }
; #define PG8_BAR __builtin_amdgcn_s_barrier()
; template <class Epi, bool ALIGN_EPI, bool SP2, class Hook>
; __device__ __forceinline__ void gemm_phase(LAS unsigned char* lds, const Gemm g, const StaticOrder& S, const Epi& E, Acc& acc, const bool fresh, const Hook& H, const int wave_id) {
;     ...
;     const int aoff = lds_byte(wr * 64 + fr, fq * 8), boff = lds_byte(wc * 32 + fr, fq * 8);
;     ...
;     Unit cur, nxt; int ui = 0, rs_pm = -1, t0 = 0;
;     if (!S.next(0, cur)) return;
;     if (fresh) {
; #pragma unroll
;         for (int a = 0; a < 2; ++a)
; #pragma unroll
;             for (int b = 0; b < 2; ++b)
; #pragma unroll
;                 for (int m = 0; m < 4; ++m)
; #pragma unroll
;                     for (int n = 0; n < 2; ++n) acc[a][b][m][n] = (f32x4){0.f, 0.f, 0.f, 0.f};
;     }
;     bf16x8 At[4][2], B0[2][2], B1[2][2];
;     Src cA = make_src(selA(g, cur.seg), (size_t)cur.pm * tstepA), cB = make_src(selB(g, cur.seg), (size_t)cur.pn * tstep);
;     if constexpr (SP2) {
;         f32x4 rpa = {0.f, 0.f, 0.f, 0.f}, rpb = rpa;
;         float rsum = 0.f;
;         if constexpr (Epi::NEEDS_RS) { const GAS f32x4* p = (const GAS f32x4*)(E.rowss + (size_t)(cur.pm * BM + (tid >> 1)) * 16) + (tid & 1) * 2; rpa = p[0]; rpb = p[1]; }
;         PG8_STAGE(PG8_SB(0, 0), cB, voffB); PG8_STAGE(PG8_SB(0, 1), cB + hstep, voffB); PG8_STAGE(PG8_SA(0, 0), cA, voffA); PG8_STAGE(PG8_SA(0, 1), cA + hstepA, voffA);
;         if (wr == 1) PG8_BAR;
;         PG8_WAIT_V(2); PG8_BAR;
;         if constexpr (Epi::NEEDS_RS) {
;             rsum = ((rpa[0] + rpa[1]) + (rpa[2] + rpa[3])) + ((rpb[0] + rpb[1]) + (rpb[2] + rpb[3]));
;             const float t2 = __builtin_bit_cast(float, __builtin_amdgcn_update_dpp(0, __builtin_bit_cast(int, rsum), 0xB1  , 0xf, 0xf, false)); rsum = (tid & 1) ? (t2 + rsum) : (rsum + t2);
;             if ((tid & 1) == 0) ((LAS float*)(lds + RSTAB_OFF))[tid >> 1] = __builtin_amdgcn_rsqf(rsum * (1.0f / DM) + NORM_EPS);
;             rs_pm = cur.pm;
;         }
;         PG8_STAGE(PG8_SB(1, 0), cB + kstep, voffB); PG8_STAGE(PG8_SA(1, 0), cA + kstep, voffA); PG8_STAGE(PG8_SB(1, 1), cB + hstep + kstep, voffB);
;         PG8_WAIT_V(6); PG8_BAR;
.LBB0_1451:
	s_or_b64 exec, exec, s[2:3]
	s_mov_b32 m0, s39
	v_readlane_b32 s2, v254, 2
	s_mov_b32 s14, s78
	s_mov_b32 s15, s79
	v_and_b32_e32 v0, 15, v10
	v_and_b32_e32 v3, 48, v10
	v_readlane_b32 s53, v253, 62
	buffer_load_dwordx4 v133, s[76:79], s2 offen lds
	s_mov_b32 m0, s40
	s_mov_b32 s16, 0
	buffer_load_dwordx4 v135, s[76:79], s2 offen lds
	s_mov_b32 m0, s41
	v_readlane_b32 s2, v254, 4
	v_readlane_b32 s52, v253, 61
	s_mov_b32 s35, s53
	s_mov_b64 s[28:29], s[78:79]
	v_readlane_b32 s17, v254, 5
	v_readlane_b32 s18, v254, 3
	buffer_load_dwordx4 v132, s[12:15], s2 offen lds
	s_mov_b32 m0, s33
	s_mov_b32 s30, 0
	buffer_load_dwordx4 v134, s[12:15], s2 offen lds
	s_mov_b32 m0, s43
	v_readlane_b32 s2, v254, 6
	s_mov_b64 s[14:15], s[78:79]
	s_nop 3
	buffer_load_dwordx4 v133, s[76:79], s2 offen lds
	s_mov_b32 m0, s42
	s_nop 0
	buffer_load_dwordx4 v135, s[76:79], s2 offen lds
	v_readlane_b32 s2, v250, 1
	s_waitcnt vmcnt(6)
	s_barrier
	s_nop 0
	v_or_b32_e32 v2, s2, v0
	v_lshlrev_b32_e32 v4, 6, v2
	s_movk_i32 s2, 0x3c0
	v_lshlrev_b32_e32 v2, 2, v2
	v_and_or_b32 v4, v4, s2, v3
	v_and_b32_e32 v2, 32, v2
	v_readlane_b32 s2, v250, 2
	v_lshl_or_b32 v0, v0, 6, v3
	v_mov_b32_e32 v3, v1
	v_bitop3_b32 v4, v4, s2, v2 bitop3:0xde
	v_lshlrev_b32_e32 v2, 2, v10
	v_and_b32_e32 v2, 32, v2
	v_readlane_b32 s2, v253, 4
	v_add_u32_e32 v137, 0, v4
	s_nop 0
	v_bitop3_b32 v5, v0, s2, v2 bitop3:0xde
	v_mov_b32_e32 v2, v1
	v_mov_b32_e32 v0, v1
	v_add_u32_e32 v136, 0, v5
	v_mov_b64_e32 v[10:11], v[2:3]
	v_mov_b64_e32 v[18:19], v[2:3]
	v_mov_b64_e32 v[26:27], v[2:3]
	v_mov_b64_e32 v[34:35], v[2:3]
	v_mov_b64_e32 v[42:43], v[2:3]
	v_mov_b64_e32 v[50:51], v[2:3]
	v_mov_b64_e32 v[58:59], v[2:3]
	v_mov_b64_e32 v[74:75], v[2:3]
	v_mov_b64_e32 v[6:7], v[2:3]
	v_mov_b64_e32 v[14:15], v[2:3]
	v_mov_b64_e32 v[22:23], v[2:3]
	v_mov_b64_e32 v[30:31], v[2:3]
	v_mov_b64_e32 v[38:39], v[2:3]
	v_mov_b64_e32 v[46:47], v[2:3]
	v_mov_b64_e32 v[54:55], v[2:3]
	v_mov_b64_e32 v[62:63], v[2:3]
	v_mov_b64_e32 v[70:71], v[2:3]
	v_mov_b64_e32 v[82:83], v[2:3]
	v_mov_b64_e32 v[90:91], v[2:3]
	v_mov_b64_e32 v[98:99], v[2:3]
	v_mov_b64_e32 v[106:107], v[2:3]
	v_mov_b64_e32 v[114:115], v[2:3]
	v_mov_b64_e32 v[122:123], v[2:3]
	v_mov_b64_e32 v[130:131], v[2:3]
	v_mov_b64_e32 v[66:67], v[2:3]
	v_mov_b64_e32 v[78:79], v[2:3]
	v_mov_b64_e32 v[86:87], v[2:3]
	v_mov_b64_e32 v[94:95], v[2:3]
	v_mov_b64_e32 v[102:103], v[2:3]
	v_mov_b64_e32 v[110:111], v[2:3]
	v_mov_b64_e32 v[118:119], v[2:3]
	v_mov_b64_e32 v[126:127], v[2:3]
	v_mov_b64_e32 v[8:9], v[0:1]
	v_mov_b64_e32 v[16:17], v[0:1]
	v_mov_b64_e32 v[24:25], v[0:1]
	v_mov_b64_e32 v[32:33], v[0:1]
	v_mov_b64_e32 v[40:41], v[0:1]
	v_mov_b64_e32 v[48:49], v[0:1]
	v_mov_b64_e32 v[56:57], v[0:1]
	v_mov_b64_e32 v[72:73], v[0:1]
	v_mov_b64_e32 v[4:5], v[0:1]
	v_mov_b64_e32 v[12:13], v[0:1]
	v_mov_b64_e32 v[20:21], v[0:1]
	v_mov_b64_e32 v[28:29], v[0:1]
	v_mov_b64_e32 v[36:37], v[0:1]
	v_mov_b64_e32 v[44:45], v[0:1]
	v_mov_b64_e32 v[52:53], v[0:1]
	v_mov_b64_e32 v[60:61], v[0:1]
	v_mov_b64_e32 v[68:69], v[0:1]
	v_mov_b64_e32 v[80:81], v[0:1]
	v_mov_b64_e32 v[88:89], v[0:1]
	v_mov_b64_e32 v[96:97], v[0:1]
	v_mov_b64_e32 v[104:105], v[0:1]
	v_mov_b64_e32 v[112:113], v[0:1]
	v_mov_b64_e32 v[120:121], v[0:1]
	v_mov_b64_e32 v[128:129], v[0:1]
	v_mov_b64_e32 v[64:65], v[0:1]
	v_mov_b64_e32 v[76:77], v[0:1]
	v_mov_b64_e32 v[84:85], v[0:1]
	v_mov_b64_e32 v[92:93], v[0:1]
	v_mov_b64_e32 v[100:101], v[0:1]
	v_mov_b64_e32 v[108:109], v[0:1]
	v_mov_b64_e32 v[116:117], v[0:1]
	v_mov_b64_e32 v[124:125], v[0:1]
	s_branch .LBB0_1454
	.p2align	6

; template <class Epi, bool ALIGN_EPI, bool SP2, class Hook>
; __device__ __forceinline__ void gemm_phase(LAS unsigned char* lds, const Gemm g, const StaticOrder& S, const Epi& E, Acc& acc, const bool fresh, const Hook& H, const int wave_id) {
;     ...
;         for (int t = t0; t < nt; t += 2) {
;             const bool last = (t == nt - 2);
;             const Src a1 = cA + (size_t)(t + 1) * kstep;
;             const Src a2 = last ? nA : cA + (size_t)(t + 2) * kstep, b2 = last ? nB : cB + (size_t)(t + 2) * kstep;
;             const Src a3 = a2 + kstep, b3 = b2 + kstep;
.LBB0_1460:
	s_add_i32 s54, s16, -2
	s_lshl_b32 s16, s16, 7
	s_add_i32 s18, s18, s16
	s_add_i32 s16, s17, s16
	s_add_i32 s55, s18, 0x40080
	s_add_i32 s56, s16, 0x100
	.p2align	6

; template <class Epi, bool ALIGN_EPI, bool SP2, class Hook>
; __device__ __forceinline__ void gemm_phase(LAS unsigned char* lds, const Gemm g, const StaticOrder& S, const Epi& E, Acc& acc, const bool fresh, const Hook& H, const int wave_id) {
;     ...
;         if (reset) {
; #pragma unroll
;             for (int a = 0; a < 2; ++a)
; #pragma unroll
;                 for (int b = 0; b < 2; ++b)
; #pragma unroll
;                     for (int m = 0; m < 4; ++m)
; #pragma unroll
;                         for (int n = 0; n < 2; ++n) acc[a][b][m][n] = (f32x4){0.f, 0.f, 0.f, 0.f};
;         }
.LBB0_1571:
	v_mov_b32_e32 v2, 0
	s_add_i32 s2, s17, 0xc0080
	s_add_i32 s3, s16, 0x100
	s_mov_b32 s61, -2
	v_mov_b32_e32 v3, v2
	v_mov_b32_e32 v4, v2
	v_mov_b32_e32 v5, v2
	v_mov_b32_e32 v6, v2
	v_mov_b32_e32 v7, v2
	v_mov_b32_e32 v8, v2
	v_mov_b32_e32 v9, v2
	v_mov_b32_e32 v18, v2
	v_mov_b32_e32 v19, v2
	v_mov_b32_e32 v20, v2
	v_mov_b32_e32 v21, v2
	v_mov_b32_e32 v22, v2
	v_mov_b32_e32 v23, v2
	v_mov_b32_e32 v24, v2
	v_mov_b32_e32 v25, v2
	v_mov_b32_e32 v34, v2
	v_mov_b32_e32 v35, v2
	v_mov_b32_e32 v36, v2
	v_mov_b32_e32 v37, v2
	v_mov_b32_e32 v38, v2
	v_mov_b32_e32 v39, v2
	v_mov_b32_e32 v40, v2
	v_mov_b32_e32 v41, v2
	v_mov_b32_e32 v50, v2
	v_mov_b32_e32 v51, v2
	v_mov_b32_e32 v52, v2
	v_mov_b32_e32 v53, v2
	v_mov_b32_e32 v54, v2
	v_mov_b32_e32 v55, v2
	v_mov_b32_e32 v56, v2
	v_mov_b32_e32 v57, v2
	v_mov_b32_e32 v10, v2
	v_mov_b32_e32 v11, v2
	v_mov_b32_e32 v12, v2
	v_mov_b32_e32 v13, v2
	v_mov_b32_e32 v14, v2
	v_mov_b32_e32 v15, v2
	v_mov_b32_e32 v16, v2
	v_mov_b32_e32 v17, v2
	v_mov_b32_e32 v26, v2
	v_mov_b32_e32 v27, v2
	v_mov_b32_e32 v28, v2
	v_mov_b32_e32 v29, v2
	v_mov_b32_e32 v30, v2
	v_mov_b32_e32 v31, v2
	v_mov_b32_e32 v32, v2
	v_mov_b32_e32 v33, v2
	v_mov_b32_e32 v42, v2
	v_mov_b32_e32 v43, v2
	v_mov_b32_e32 v44, v2
	v_mov_b32_e32 v45, v2
	v_mov_b32_e32 v46, v2
	v_mov_b32_e32 v47, v2
	v_mov_b32_e32 v48, v2
	v_mov_b32_e32 v49, v2
	v_mov_b32_e32 v58, v2
	v_mov_b32_e32 v59, v2
	v_mov_b32_e32 v60, v2
	v_mov_b32_e32 v61, v2
	v_mov_b32_e32 v62, v2
	v_mov_b32_e32 v63, v2
	v_mov_b32_e32 v64, v2
	v_mov_b32_e32 v65, v2
	v_mov_b32_e32 v66, v2
	v_mov_b32_e32 v67, v2
	v_mov_b32_e32 v68, v2
	v_mov_b32_e32 v69, v2
	v_mov_b32_e32 v70, v2
	v_mov_b32_e32 v71, v2
	v_mov_b32_e32 v72, v2
	v_mov_b32_e32 v73, v2
	v_mov_b32_e32 v82, v2
	v_mov_b32_e32 v83, v2
	v_mov_b32_e32 v84, v2
	v_mov_b32_e32 v85, v2
	v_mov_b32_e32 v86, v2
	v_mov_b32_e32 v87, v2
	v_mov_b32_e32 v88, v2
	v_mov_b32_e32 v89, v2
	v_mov_b32_e32 v98, v2
	v_mov_b32_e32 v99, v2
	v_mov_b32_e32 v100, v2
	v_mov_b32_e32 v101, v2
	v_mov_b32_e32 v102, v2
	v_mov_b32_e32 v103, v2
	v_mov_b32_e32 v104, v2
	v_mov_b32_e32 v105, v2
	v_mov_b32_e32 v114, v2
	v_mov_b32_e32 v115, v2
	v_mov_b32_e32 v116, v2
	v_mov_b32_e32 v117, v2
	v_mov_b32_e32 v118, v2
	v_mov_b32_e32 v119, v2
	v_mov_b32_e32 v120, v2
	v_mov_b32_e32 v121, v2
	v_mov_b32_e32 v74, v2
	v_mov_b32_e32 v75, v2
	v_mov_b32_e32 v76, v2
	v_mov_b32_e32 v77, v2
	v_mov_b32_e32 v78, v2
	v_mov_b32_e32 v79, v2
	v_mov_b32_e32 v80, v2
	v_mov_b32_e32 v81, v2
	v_mov_b32_e32 v90, v2
	v_mov_b32_e32 v91, v2
	v_mov_b32_e32 v92, v2
	v_mov_b32_e32 v93, v2
	v_mov_b32_e32 v94, v2
	v_mov_b32_e32 v95, v2
	v_mov_b32_e32 v96, v2
	v_mov_b32_e32 v97, v2
	v_mov_b32_e32 v106, v2
	v_mov_b32_e32 v107, v2
	v_mov_b32_e32 v108, v2
	v_mov_b32_e32 v109, v2
	v_mov_b32_e32 v110, v2
	v_mov_b32_e32 v111, v2
	v_mov_b32_e32 v112, v2
	v_mov_b32_e32 v113, v2
	v_mov_b32_e32 v122, v2
	v_mov_b32_e32 v123, v2
	v_mov_b32_e32 v124, v2
	v_mov_b32_e32 v125, v2
	v_mov_b32_e32 v126, v2
	v_mov_b32_e32 v127, v2
	v_mov_b32_e32 v128, v2
	v_mov_b32_e32 v129, v2
	s_waitcnt vmcnt(0)
	.p2align	6

; template <class Epi, bool ALIGN_EPI, bool SP2, class Hook>
; __device__ __forceinline__ void gemm_phase(LAS unsigned char* lds, const Gemm g, const StaticOrder& S, const Epi& E, Acc& acc, const bool fresh, const Hook& H, const int wave_id) {
;     ...
;         if (reset) {
; #pragma unroll
;             for (int a = 0; a < 2; ++a)
; #pragma unroll
;                 for (int b = 0; b < 2; ++b)
; #pragma unroll
;                     for (int m = 0; m < 4; ++m)
; #pragma unroll
;                         for (int n = 0; n < 2; ++n) acc[a][b][m][n] = (f32x4){0.f, 0.f, 0.f, 0.f};
;         }
.LBB0_1613:
	v_mov_b32_e32 v2, 0
	s_add_i32 s2, s13, 0xc0080
	s_add_i32 s3, s12, 0x100
	s_mov_b32 s59, -2
	v_mov_b32_e32 v3, v2
	v_mov_b32_e32 v4, v2
	v_mov_b32_e32 v5, v2
	v_mov_b32_e32 v6, v2
	v_mov_b32_e32 v7, v2
	v_mov_b32_e32 v8, v2
	v_mov_b32_e32 v9, v2
	v_mov_b32_e32 v18, v2
	v_mov_b32_e32 v19, v2
	v_mov_b32_e32 v20, v2
	v_mov_b32_e32 v21, v2
	v_mov_b32_e32 v22, v2
	v_mov_b32_e32 v23, v2
	v_mov_b32_e32 v24, v2
	v_mov_b32_e32 v25, v2
	v_mov_b32_e32 v34, v2
	v_mov_b32_e32 v35, v2
	v_mov_b32_e32 v36, v2
	v_mov_b32_e32 v37, v2
	v_mov_b32_e32 v38, v2
	v_mov_b32_e32 v39, v2
	v_mov_b32_e32 v40, v2
	v_mov_b32_e32 v41, v2
	v_mov_b32_e32 v50, v2
	v_mov_b32_e32 v51, v2
	v_mov_b32_e32 v52, v2
	v_mov_b32_e32 v53, v2
	v_mov_b32_e32 v54, v2
	v_mov_b32_e32 v55, v2
	v_mov_b32_e32 v56, v2
	v_mov_b32_e32 v57, v2
	v_mov_b32_e32 v10, v2
	v_mov_b32_e32 v11, v2
	v_mov_b32_e32 v12, v2
	v_mov_b32_e32 v13, v2
	v_mov_b32_e32 v14, v2
	v_mov_b32_e32 v15, v2
	v_mov_b32_e32 v16, v2
	v_mov_b32_e32 v17, v2
	v_mov_b32_e32 v26, v2
	v_mov_b32_e32 v27, v2
	v_mov_b32_e32 v28, v2
	v_mov_b32_e32 v29, v2
	v_mov_b32_e32 v30, v2
	v_mov_b32_e32 v31, v2
	v_mov_b32_e32 v32, v2
	v_mov_b32_e32 v33, v2
	v_mov_b32_e32 v42, v2
	v_mov_b32_e32 v43, v2
	v_mov_b32_e32 v44, v2
	v_mov_b32_e32 v45, v2
	v_mov_b32_e32 v46, v2
	v_mov_b32_e32 v47, v2
	v_mov_b32_e32 v48, v2
	v_mov_b32_e32 v49, v2
	v_mov_b32_e32 v58, v2
	v_mov_b32_e32 v59, v2
	v_mov_b32_e32 v60, v2
	v_mov_b32_e32 v61, v2
	v_mov_b32_e32 v62, v2
	v_mov_b32_e32 v63, v2
	v_mov_b32_e32 v64, v2
	v_mov_b32_e32 v65, v2
	v_mov_b32_e32 v66, v2
	v_mov_b32_e32 v67, v2
	v_mov_b32_e32 v68, v2
	v_mov_b32_e32 v69, v2
	v_mov_b32_e32 v70, v2
	v_mov_b32_e32 v71, v2
	v_mov_b32_e32 v72, v2
	v_mov_b32_e32 v73, v2
	v_mov_b32_e32 v82, v2
	v_mov_b32_e32 v83, v2
	v_mov_b32_e32 v84, v2
	v_mov_b32_e32 v85, v2
	v_mov_b32_e32 v86, v2
	v_mov_b32_e32 v87, v2
	v_mov_b32_e32 v88, v2
	v_mov_b32_e32 v89, v2
	v_mov_b32_e32 v98, v2
	v_mov_b32_e32 v99, v2
	v_mov_b32_e32 v100, v2
	v_mov_b32_e32 v101, v2
	v_mov_b32_e32 v102, v2
	v_mov_b32_e32 v103, v2
	v_mov_b32_e32 v104, v2
	v_mov_b32_e32 v105, v2
	v_mov_b32_e32 v114, v2
	v_mov_b32_e32 v115, v2
	v_mov_b32_e32 v116, v2
	v_mov_b32_e32 v117, v2
	v_mov_b32_e32 v118, v2
	v_mov_b32_e32 v119, v2
	v_mov_b32_e32 v120, v2
	v_mov_b32_e32 v121, v2
	v_mov_b32_e32 v74, v2
	v_mov_b32_e32 v75, v2
	v_mov_b32_e32 v76, v2
	v_mov_b32_e32 v77, v2
	v_mov_b32_e32 v78, v2
	v_mov_b32_e32 v79, v2
	v_mov_b32_e32 v80, v2
	v_mov_b32_e32 v81, v2
	v_mov_b32_e32 v90, v2
	v_mov_b32_e32 v91, v2
	v_mov_b32_e32 v92, v2
	v_mov_b32_e32 v93, v2
	v_mov_b32_e32 v94, v2
	v_mov_b32_e32 v95, v2
	v_mov_b32_e32 v96, v2
	v_mov_b32_e32 v97, v2
	v_mov_b32_e32 v106, v2
	v_mov_b32_e32 v107, v2
	v_mov_b32_e32 v108, v2
	v_mov_b32_e32 v109, v2
	v_mov_b32_e32 v110, v2
	v_mov_b32_e32 v111, v2
	v_mov_b32_e32 v112, v2
	v_mov_b32_e32 v113, v2
	v_mov_b32_e32 v122, v2
	v_mov_b32_e32 v123, v2
	v_mov_b32_e32 v124, v2
	v_mov_b32_e32 v125, v2
	v_mov_b32_e32 v126, v2
	v_mov_b32_e32 v127, v2
	v_mov_b32_e32 v128, v2
	v_mov_b32_e32 v129, v2
	s_waitcnt vmcnt(0)
	.p2align	6
